# same-XCD group barrier: returning arrival atomic + agent-scope L1 invalidate issued right behind it (latencies overlap, workgroup parked, polls are sc1); last arriver skips the poll
# baseline (speedup 1.0000x reference)
.LBB0_932:
	v_readlane_b32 s8, v254, 30
	s_add_i32 s8, s8, 1
	v_cmp_eq_u32_e32 vcc, 0, v0
	v_readlane_b32 s0, v250, 13
	v_writelane_b32 v254, s8, 30
	s_mul_i32 s14, s8, s0
	s_cbranch_vccnz .LBB0_946
	s_waitcnt vmcnt(0)
	v_readlane_b32 s0, v250, 6
	v_readlane_b32 s1, v250, 7
	s_waitcnt vmcnt(0) lgkmcnt(0)
	s_barrier
	s_and_saveexec_b64 s[8:9], s[0:1]
	s_cbranch_execz .LBB0_945
	s_mov_b64 s[12:13], exec
	v_mbcnt_lo_u32_b32 v0, s12, 0
	v_mbcnt_hi_u32_b32 v0, s13, v0
	v_cmp_eq_u32_e32 vcc, 0, v0
	s_and_saveexec_b64 s[10:11], vcc
	s_cbranch_execz .LBB0_936
	s_bcnt1_i32_b64 s12, s[12:13]
	v_mov_b32_e32 v0, s12
	global_atomic_add v0, v181, v0, s[28:29] sc0
	buffer_inv sc1
	s_waitcnt vmcnt(0)
	v_add_u32_e32 v0, s12, v0
	v_cmp_le_u32_e32 vcc, s14, v0
	s_cbranch_vccnz .LBB0_944

.LBB0_944:
	s_nop 0
	s_waitcnt vmcnt(0)
